# P6 up GEMM: 512 sample rows as one 128x128 tile per WG up front (new hand-written loop), 256x256 schedule reduced to 64 row panels = exactly 8 units per WG
# speedup vs baseline: 1.0084x; 1.0084x over previous
; #define LBAR() asm volatile("s_waitcnt lgkmcnt(0)\n\ts_barrier" ::: "memory")
; #define SG_LOAD(k0) do { _Pragma("unroll") for (int i_ = 0; i_ < 4; ++i_) { const int id_ = tid + i_ * 512, rr_ = id_ >> 5, cc_ = id_ & 31; \
;         ra[i_] = *(const u32x4*)(Ag + (size_t)rr_ * lda + (k0) + cc_ * 8); rb[i_] = *(const u32x4*)(Bg + (size_t)rr_ * ldb + (k0) + cc_ * 8); } } while (0)
; template <class Epi>
; __device__ __forceinline__ void small_gemm_tile(unsigned char* lds, const bf16_t* A, int lda, const bf16_t* Bt, int ldb, int K, int kbreak, int rowbase, int tm, int tn, const Epi& E, int tid) {
;     const int lane = tid & 63, wave = tid >> 6, r16 = lane & 15, q4 = lane >> 4, wm = wave >> 1, wn = wave & 1;
;     unsigned char* AS = lds; unsigned char* BS = lds + 33792; float* RED = (float*)(lds + 67584);
;     const bf16_t* Ag = A + (size_t)(rowbase + tm * 64) * lda; const bf16_t* Bg = Bt + (size_t)(tn * 64) * ldb;
;     u32x4 ra[4], rb[4];
;     ...
;     f32x4 cur[2], first[2];
; #pragma unroll
;     for (int n_ = 0; n_ < 2; ++n_) { cur[n_] = (f32x4){0.f, 0.f, 0.f, 0.f}; first[n_] = (f32x4){0.f, 0.f, 0.f, 0.f}; }
;     SG_LOAD(0);
;     for (int k0 = 0; k0 < K; k0 += 256) {
; #pragma unroll
;         for (int i = 0; i < 4; ++i) { const int id = tid + i * 512, rr = id >> 5, cc = id & 31; *(u32x4*)(AS + rr * 528 + cc * 16) = ra[i]; *(u32x4*)(BS + rr * 528 + cc * 16) = rb[i]; }
;         LBAR();
;         if (k0 + 256 < K) SG_LOAD(k0 + 256);
;         if (k0 == kbreak) {
; #pragma unroll
;             for (int n_ = 0; n_ < 2; ++n_) { first[n_] = cur[n_]; cur[n_] = (f32x4){0.f, 0.f, 0.f, 0.f}; } }
; #pragma unroll
;         for (int kk = 0; kk < 8; ++kk) { const bf16x8 af = *(const bf16x8*)(AS + (wm * 16 + r16) * 528 + kk * 64 + q4 * 16);
; #pragma unroll
;             for (int nt = 0; nt < 2; ++nt) { const bf16x8 bfg = *(const bf16x8*)(BS + (wn * 32 + nt * 16 + r16) * 528 + kk * 64 + q4 * 16); cur[nt] = __builtin_amdgcn_mfma_f32_16x16x32_bf16(bfg, af, cur[nt], 0, 0, 0); } }
;         LBAR();
;     }
; __global__ void __launch_bounds__(512, 2) hybrid_fwd(Args a) {
;     ...
;         pg8::Gemm g{X1B, WUP, M, DFF, DM, DM, DM}; pg8::StaticOrder S; S.init(M, DFF, G, bx);
;         pg8::EpiScaleBf16<1> E{HID, DFF, SS1}; pg8::gemm_phase<pg8::EpiScaleBf16<1>, pg8::StaticOrder>(ldsl, g, S, E); } SEAM(6);
.LBB0_924:
	s_or_b64 exec, exec, s[0:1]
	s_cmpk_gt_i32 s2, 0x7ff
	v_readfirstlane_b32 s5, v188
	s_waitcnt lgkmcnt(0)
	s_barrier
	s_cbranch_scc1 .LBB0_940
	v_lshrrev_b32_e32 v126, 3, v188
	v_and_b32_e32 v127, 7, v188
	s_and_b32 s4, s2, 7
	s_lshr_b32 s34, s2, 3
	s_and_b32 s35, s34, 3
	s_lshr_b32 s34, s34, 2
	s_lshl_b32 s34, s34, 3
	s_add_i32 s34, s34, s4
	s_lshl_b32 s8, s35, 19
	s_add_u32 s10, s86, 0x2ef00000
	s_addc_u32 s11, s87, 0
	s_add_u32 s10, s10, 0x4000000
	s_addc_u32 s11, s11, 0
	s_add_u32 s10, s10, s8
	s_addc_u32 s11, s11, 0
	s_lshl_b32 s9, s34, 19
	s_add_u32 s14, s86, 0x4400000
	s_addc_u32 s15, s87, 0
	s_add_u32 s14, s14, s9
	s_addc_u32 s15, s15, 0
	v_lshlrev_b32_e32 v128, 12, v126
	v_lshl_add_u32 v128, v127, 4, v128
	v_mov_b32_e32 v129, 0
	s_mov_b64 s[16:17], 0x40000
	s_mov_b64 s[18:19], 0x80
	v_lshl_add_u64 v[112:113], s[10:11], 0, v[128:129]
	v_lshl_add_u64 v[114:115], v[112:113], 0, s[16:17]
	v_lshl_add_u64 v[116:117], s[14:15], 0, v[128:129]
	v_lshl_add_u64 v[118:119], v[116:117], 0, s[16:17]
	v_mul_u32_u24_e32 v120, 0xa0, v126
	v_lshl_add_u32 v120, v127, 4, v120
	v_add_u32_e32 v121, 0xa000, v120
	v_and_b32_e32 v130, 3, v126
	v_bfe_u32 v131, v126, 2, 1
	v_bfe_u32 v132, v126, 3, 2
	v_lshrrev_b32_e32 v133, 5, v126
	v_lshl_add_u32 v130, v131, 4, v130
	v_lshl_add_u32 v130, v132, 2, v130
	v_lshl_add_u32 v130, v133, 5, v130
	v_mul_u32_u24_e32 v122, 0xa0, v130
	v_lshl_add_u32 v122, v127, 4, v122
	v_add_u32_e32 v122, 0x5000, v122
	v_add_u32_e32 v123, 0xa000, v122
	v_and_b32_e32 v134, 15, v188
	v_bfe_u32 v135, v188, 4, 2
	v_bfe_u32 v136, v188, 8, 1
	v_bfe_u32 v137, v188, 6, 2
	v_lshl_add_u32 v138, v136, 6, v134
	v_mul_u32_u24_e32 v124, 0xa0, v138
	v_lshl_add_u32 v124, v135, 4, v124
	v_add_u32_e32 v125, 0xa000, v124
	v_lshl_add_u32 v139, v137, 5, v134
	v_mul_u32_u24_e32 v140, 0xa0, v139
	v_lshl_add_u32 v140, v135, 4, v140
	v_add_u32_e32 v140, 0x5000, v140
	v_add_u32_e32 v141, 0xa000, v140
	s_mov_b32 s36, 16
	v_mov_b32_e32 v0, 0
	v_mov_b32_e32 v1, 0
	v_mov_b32_e32 v2, 0
	v_mov_b32_e32 v3, 0
	v_mov_b32_e32 v4, 0
	v_mov_b32_e32 v5, 0
	v_mov_b32_e32 v6, 0
	v_mov_b32_e32 v7, 0
	v_mov_b32_e32 v8, 0
	v_mov_b32_e32 v9, 0
	v_mov_b32_e32 v10, 0
	v_mov_b32_e32 v11, 0
	v_mov_b32_e32 v12, 0
	v_mov_b32_e32 v13, 0
	v_mov_b32_e32 v14, 0
	v_mov_b32_e32 v15, 0
	v_mov_b32_e32 v16, 0
	v_mov_b32_e32 v17, 0
	v_mov_b32_e32 v18, 0
	v_mov_b32_e32 v19, 0
	v_mov_b32_e32 v20, 0
	v_mov_b32_e32 v21, 0
	v_mov_b32_e32 v22, 0
	v_mov_b32_e32 v23, 0
	v_mov_b32_e32 v24, 0
	v_mov_b32_e32 v25, 0
	v_mov_b32_e32 v26, 0
	v_mov_b32_e32 v27, 0
	v_mov_b32_e32 v28, 0
	v_mov_b32_e32 v29, 0
	v_mov_b32_e32 v30, 0
	v_mov_b32_e32 v31, 0
	global_load_dwordx4 v[32:35], v[112:113], off
	global_load_dwordx4 v[36:39], v[114:115], off
	global_load_dwordx4 v[40:43], v[116:117], off
	global_load_dwordx4 v[44:47], v[118:119], off
	v_lshl_add_u64 v[112:113], v[112:113], 0, s[18:19]
	v_lshl_add_u64 v[114:115], v[114:115], 0, s[18:19]
	v_lshl_add_u64 v[116:117], v[116:117], 0, s[18:19]
	v_lshl_add_u64 v[118:119], v[118:119], 0, s[18:19]
	global_load_dwordx4 v[48:51], v[112:113], off
	global_load_dwordx4 v[52:55], v[114:115], off
	global_load_dwordx4 v[56:59], v[116:117], off
	global_load_dwordx4 v[60:63], v[118:119], off
	v_lshl_add_u64 v[112:113], v[112:113], 0, s[18:19]
	v_lshl_add_u64 v[114:115], v[114:115], 0, s[18:19]
	v_lshl_add_u64 v[116:117], v[116:117], 0, s[18:19]
	v_lshl_add_u64 v[118:119], v[118:119], 0, s[18:19]
	s_waitcnt vmcnt(4)
	ds_write_b128 v120, v[32:35]
	ds_write_b128 v120, v[36:39] offset:10240
	ds_write_b128 v122, v[40:43]
	ds_write_b128 v122, v[44:47] offset:10240
	global_load_dwordx4 v[32:35], v[112:113], off
	global_load_dwordx4 v[36:39], v[114:115], off
	global_load_dwordx4 v[40:43], v[116:117], off
	global_load_dwordx4 v[44:47], v[118:119], off
	v_lshl_add_u64 v[112:113], v[112:113], 0, s[18:19]
	v_lshl_add_u64 v[114:115], v[114:115], 0, s[18:19]
	v_lshl_add_u64 v[116:117], v[116:117], 0, s[18:19]
	v_lshl_add_u64 v[118:119], v[118:119], 0, s[18:19]
	s_waitcnt lgkmcnt(0)
	s_barrier
.Lp6s_loop:
	s_waitcnt vmcnt(4)
	ds_write_b128 v121, v[48:51]
	ds_write_b128 v121, v[52:55] offset:10240
	ds_write_b128 v123, v[56:59]
	ds_write_b128 v123, v[60:63] offset:10240
	global_load_dwordx4 v[48:51], v[112:113], off
	global_load_dwordx4 v[52:55], v[114:115], off
	global_load_dwordx4 v[56:59], v[116:117], off
	global_load_dwordx4 v[60:63], v[118:119], off
	v_lshl_add_u64 v[112:113], v[112:113], 0, s[18:19]
	v_lshl_add_u64 v[114:115], v[114:115], 0, s[18:19]
	v_lshl_add_u64 v[116:117], v[116:117], 0, s[18:19]
	v_lshl_add_u64 v[118:119], v[118:119], 0, s[18:19]
	ds_read_b128 v[80:83], v140
	ds_read_b128 v[84:87], v140 offset:2560
	ds_read_b128 v[64:67], v124
	ds_read_b128 v[68:71], v124 offset:2560
	ds_read_b128 v[72:75], v124 offset:5120
	ds_read_b128 v[76:79], v124 offset:7680
	ds_read_b128 v[104:107], v140 offset:64
	ds_read_b128 v[108:111], v140 offset:2624
	ds_read_b128 v[88:91], v124 offset:64
	ds_read_b128 v[92:95], v124 offset:2624
	ds_read_b128 v[96:99], v124 offset:5184
	s_waitcnt lgkmcnt(10)
	s_waitcnt lgkmcnt(8)
	ds_read_b128 v[100:103], v124 offset:7744
	v_mfma_f32_16x16x32_bf16 v[0:3], v[80:83], v[64:67], v[0:3]
	v_mfma_f32_16x16x32_bf16 v[4:7], v[84:87], v[64:67], v[4:7]
	s_waitcnt lgkmcnt(8)
	v_mfma_f32_16x16x32_bf16 v[8:11], v[80:83], v[68:71], v[8:11]
	v_mfma_f32_16x16x32_bf16 v[12:15], v[84:87], v[68:71], v[12:15]
	s_waitcnt lgkmcnt(7)
	v_mfma_f32_16x16x32_bf16 v[16:19], v[80:83], v[72:75], v[16:19]
	v_mfma_f32_16x16x32_bf16 v[20:23], v[84:87], v[72:75], v[20:23]
	s_waitcnt lgkmcnt(6)
	v_mfma_f32_16x16x32_bf16 v[24:27], v[80:83], v[76:79], v[24:27]
	v_mfma_f32_16x16x32_bf16 v[28:31], v[84:87], v[76:79], v[28:31]
	s_waitcnt lgkmcnt(5)
	s_waitcnt lgkmcnt(3)
	v_mfma_f32_16x16x32_bf16 v[0:3], v[104:107], v[88:91], v[0:3]
	v_mfma_f32_16x16x32_bf16 v[4:7], v[108:111], v[88:91], v[4:7]
	s_waitcnt lgkmcnt(2)
	v_mfma_f32_16x16x32_bf16 v[8:11], v[104:107], v[92:95], v[8:11]
	v_mfma_f32_16x16x32_bf16 v[12:15], v[108:111], v[92:95], v[12:15]
	s_waitcnt lgkmcnt(1)
	v_mfma_f32_16x16x32_bf16 v[16:19], v[104:107], v[96:99], v[16:19]
	v_mfma_f32_16x16x32_bf16 v[20:23], v[108:111], v[96:99], v[20:23]
	s_waitcnt lgkmcnt(0)
	v_mfma_f32_16x16x32_bf16 v[24:27], v[104:107], v[100:103], v[24:27]
	v_mfma_f32_16x16x32_bf16 v[28:31], v[108:111], v[100:103], v[28:31]
	s_waitcnt lgkmcnt(0)
	s_barrier
; __device__ __forceinline__ unsigned cvt_pk_bf16(float lo, float hi) { unsigned r; asm volatile("v_cvt_pk_bf16_f32 %0, %1, %2" : "=v"(r) : "v"(lo), "v"(hi)); return r; }
;     __device__ __forceinline__ void operator()(const f32x4 (&acc)[2][2][4][2], const Unit& u, int wr, int wc, int fr, int fq) const {
;         const int row0 = u.pm * BM + wr * 64 + fr, col0 = u.pn * BM + wc * 32 + 8 * fq;
; #pragma unroll
;         for (int ai = 0; ai < 2; ++ai)
; #pragma unroll
;             for (int m = 0; m < 4; ++m) { const int row = row0 + ai * HALF + m * 16; const float rs = ACT == 1 ? ss[row] : 1.0f;
;                 bf16_t* rowp = O + (size_t)row * ldc + col0;
; #pragma unroll
;                 for (int bj = 0; bj < 2; ++bj) { f32x4 v0 = acc[ai][bj][m][0] * rs, v1 = acc[ai][bj][m][1] * rs;
;                     if (ACT == 1) {
; #pragma unroll
;                         for (int e = 0; e < 4; ++e) { const float a0 = fmaxf(v0[e], 0.f), a1 = fmaxf(v1[e], 0.f); v0[e] = a0 * a0; v1[e] = a1 * a1; } }
;                     u32x4 w; w.x = cvt_pk_bf16(v0[0], v0[1]); w.y = cvt_pk_bf16(v0[2], v0[3]); w.z = cvt_pk_bf16(v1[0], v1[1]); w.w = cvt_pk_bf16(v1[2], v1[3]);
;                     *(u32x4*)(rowp + bj * HALF) = w; } }
; template <class Epi>
; __device__ __forceinline__ void small_gemm_tile(unsigned char* lds, const bf16_t* A, int lda, const bf16_t* Bt, int ldb, int K, int kbreak, int rowbase, int tm, int tn, const Epi& E, int tid) {
;     ...
;     for (int k0 = 0; k0 < K; k0 += 256) {
; #pragma unroll
;         for (int i = 0; i < 4; ++i) { const int id = tid + i * 512, rr = id >> 5, cc = id & 31; *(u32x4*)(AS + rr * 528 + cc * 16) = ra[i]; *(u32x4*)(BS + rr * 528 + cc * 16) = rb[i]; }
;         LBAR();
;         if (k0 + 256 < K) SG_LOAD(k0 + 256);
;         if (k0 == kbreak) {
; #pragma unroll
;             for (int n_ = 0; n_ < 2; ++n_) { first[n_] = cur[n_]; cur[n_] = (f32x4){0.f, 0.f, 0.f, 0.f}; } }
; #pragma unroll
;         for (int kk = 0; kk < 8; ++kk) { const bf16x8 af = *(const bf16x8*)(AS + (wm * 16 + r16) * 528 + kk * 64 + q4 * 16);
; #pragma unroll
;             for (int nt = 0; nt < 2; ++nt) { const bf16x8 bfg = *(const bf16x8*)(BS + (wn * 32 + nt * 16 + r16) * 528 + kk * 64 + q4 * 16); cur[nt] = __builtin_amdgcn_mfma_f32_16x16x32_bf16(bfg, af, cur[nt], 0, 0, 0); } }
;         LBAR();
;     }
	s_waitcnt vmcnt(4)
	ds_write_b128 v120, v[32:35]
	ds_write_b128 v120, v[36:39] offset:10240
	ds_write_b128 v122, v[40:43]
	ds_write_b128 v122, v[44:47] offset:10240
	global_load_dwordx4 v[32:35], v[112:113], off
	global_load_dwordx4 v[36:39], v[114:115], off
	global_load_dwordx4 v[40:43], v[116:117], off
	global_load_dwordx4 v[44:47], v[118:119], off
	v_lshl_add_u64 v[112:113], v[112:113], 0, s[18:19]
	v_lshl_add_u64 v[114:115], v[114:115], 0, s[18:19]
	v_lshl_add_u64 v[116:117], v[116:117], 0, s[18:19]
	v_lshl_add_u64 v[118:119], v[118:119], 0, s[18:19]
	ds_read_b128 v[80:83], v141
	ds_read_b128 v[84:87], v141 offset:2560
	ds_read_b128 v[64:67], v125
	ds_read_b128 v[68:71], v125 offset:2560
	ds_read_b128 v[72:75], v125 offset:5120
	ds_read_b128 v[76:79], v125 offset:7680
	ds_read_b128 v[104:107], v141 offset:64
	ds_read_b128 v[108:111], v141 offset:2624
	ds_read_b128 v[88:91], v125 offset:64
	ds_read_b128 v[92:95], v125 offset:2624
	ds_read_b128 v[96:99], v125 offset:5184
	s_waitcnt lgkmcnt(10)
	s_waitcnt lgkmcnt(8)
	ds_read_b128 v[100:103], v125 offset:7744
	v_mfma_f32_16x16x32_bf16 v[0:3], v[80:83], v[64:67], v[0:3]
	v_mfma_f32_16x16x32_bf16 v[4:7], v[84:87], v[64:67], v[4:7]
	s_waitcnt lgkmcnt(8)
	v_mfma_f32_16x16x32_bf16 v[8:11], v[80:83], v[68:71], v[8:11]
	v_mfma_f32_16x16x32_bf16 v[12:15], v[84:87], v[68:71], v[12:15]
	s_waitcnt lgkmcnt(7)
	v_mfma_f32_16x16x32_bf16 v[16:19], v[80:83], v[72:75], v[16:19]
	v_mfma_f32_16x16x32_bf16 v[20:23], v[84:87], v[72:75], v[20:23]
	s_waitcnt lgkmcnt(6)
	v_mfma_f32_16x16x32_bf16 v[24:27], v[80:83], v[76:79], v[24:27]
	v_mfma_f32_16x16x32_bf16 v[28:31], v[84:87], v[76:79], v[28:31]
	s_waitcnt lgkmcnt(5)
	s_waitcnt lgkmcnt(3)
	v_mfma_f32_16x16x32_bf16 v[0:3], v[104:107], v[88:91], v[0:3]
	v_mfma_f32_16x16x32_bf16 v[4:7], v[108:111], v[88:91], v[4:7]
	s_waitcnt lgkmcnt(2)
	v_mfma_f32_16x16x32_bf16 v[8:11], v[104:107], v[92:95], v[8:11]
	v_mfma_f32_16x16x32_bf16 v[12:15], v[108:111], v[92:95], v[12:15]
	s_waitcnt lgkmcnt(1)
	v_mfma_f32_16x16x32_bf16 v[16:19], v[104:107], v[96:99], v[16:19]
	v_mfma_f32_16x16x32_bf16 v[20:23], v[108:111], v[96:99], v[20:23]
	s_waitcnt lgkmcnt(0)
	v_mfma_f32_16x16x32_bf16 v[24:27], v[104:107], v[100:103], v[24:27]
	v_mfma_f32_16x16x32_bf16 v[28:31], v[108:111], v[100:103], v[28:31]
	s_waitcnt lgkmcnt(0)
	s_barrier
	s_add_i32 s36, s36, -1
	s_cmp_lg_u32 s36, 0
	s_cbranch_scc1 .Lp6s_loop
	s_waitcnt vmcnt(0)
	s_nop 15
	s_nop 15
	s_lshl_b32 s8, s35, 7
	s_add_i32 s8, s8, 0x4000
	v_add_u32_e32 v142, s8, v138
	v_lshlrev_b32_e32 v143, 2, v142
	global_load_dword v144, v143, s[86:87]
	global_load_dword v145, v143, s[86:87] offset:64
	global_load_dword v146, v143, s[86:87] offset:128
	global_load_dword v147, v143, s[86:87] offset:192
	v_lshlrev_b32_e32 v150, 14, v142
	s_lshl_b32 s9, s34, 8
	v_lshlrev_b32_e32 v151, 6, v137
	v_lshl_add_u32 v151, v135, 4, v151
	v_add3_u32 v150, v150, v151, s9
	v_mov_b32_e32 v151, 0
	s_add_u32 s20, s86, 0xc600000
	s_addc_u32 s21, s87, 0
	s_mov_b64 s[22:23], 0x40000
	v_lshl_add_u64 v[152:153], s[20:21], 0, v[150:151]
	s_waitcnt vmcnt(3)
	v_mul_f32_e32 v0, v0, v144
	v_mul_f32_e32 v1, v1, v144
	v_mul_f32_e32 v2, v2, v144
	v_mul_f32_e32 v3, v3, v144
	v_max_f32_e32 v0, 0, v0
	v_max_f32_e32 v1, 0, v1
	v_max_f32_e32 v2, 0, v2
	v_max_f32_e32 v3, 0, v3
	v_mul_f32_e32 v0, v0, v0
	v_mul_f32_e32 v1, v1, v1
	v_mul_f32_e32 v2, v2, v2
	v_mul_f32_e32 v3, v3, v3
	v_mul_f32_e32 v4, v4, v144
	v_mul_f32_e32 v5, v5, v144
	v_mul_f32_e32 v6, v6, v144
	v_mul_f32_e32 v7, v7, v144
	v_max_f32_e32 v4, 0, v4
	v_max_f32_e32 v5, 0, v5
	v_max_f32_e32 v6, 0, v6
	v_max_f32_e32 v7, 0, v7
	v_mul_f32_e32 v4, v4, v4
	v_mul_f32_e32 v5, v5, v5
	v_mul_f32_e32 v6, v6, v6
	v_mul_f32_e32 v7, v7, v7
	v_cvt_pk_bf16_f32 v154, v0, v1
	v_cvt_pk_bf16_f32 v155, v2, v3
	v_cvt_pk_bf16_f32 v156, v4, v5
	v_cvt_pk_bf16_f32 v157, v6, v7
	global_store_dwordx4 v[152:153], v[154:157], off
	s_nop 1
	v_lshl_add_u64 v[152:153], v[152:153], 0, s[22:23]
	s_waitcnt vmcnt(2)
	v_mul_f32_e32 v8, v8, v145
	v_mul_f32_e32 v9, v9, v145
	v_mul_f32_e32 v10, v10, v145
	v_mul_f32_e32 v11, v11, v145
	v_max_f32_e32 v8, 0, v8
	v_max_f32_e32 v9, 0, v9
	v_max_f32_e32 v10, 0, v10
	v_max_f32_e32 v11, 0, v11
	v_mul_f32_e32 v8, v8, v8
	v_mul_f32_e32 v9, v9, v9
	v_mul_f32_e32 v10, v10, v10
	v_mul_f32_e32 v11, v11, v11
	v_mul_f32_e32 v12, v12, v145
	v_mul_f32_e32 v13, v13, v145
	v_mul_f32_e32 v14, v14, v145
	v_mul_f32_e32 v15, v15, v145
	v_max_f32_e32 v12, 0, v12
	v_max_f32_e32 v13, 0, v13
	v_max_f32_e32 v14, 0, v14
	v_max_f32_e32 v15, 0, v15
	v_mul_f32_e32 v12, v12, v12
	v_mul_f32_e32 v13, v13, v13
	v_mul_f32_e32 v14, v14, v14
	v_mul_f32_e32 v15, v15, v15
	v_cvt_pk_bf16_f32 v154, v8, v9
	v_cvt_pk_bf16_f32 v155, v10, v11
	v_cvt_pk_bf16_f32 v156, v12, v13
	v_cvt_pk_bf16_f32 v157, v14, v15
	global_store_dwordx4 v[152:153], v[154:157], off
	s_nop 1
	v_lshl_add_u64 v[152:153], v[152:153], 0, s[22:23]
	s_waitcnt vmcnt(1)
	v_mul_f32_e32 v16, v16, v146
	v_mul_f32_e32 v17, v17, v146
	v_mul_f32_e32 v18, v18, v146
	v_mul_f32_e32 v19, v19, v146
	v_max_f32_e32 v16, 0, v16
	v_max_f32_e32 v17, 0, v17
	v_max_f32_e32 v18, 0, v18
	v_max_f32_e32 v19, 0, v19
	v_mul_f32_e32 v16, v16, v16
	v_mul_f32_e32 v17, v17, v17
	v_mul_f32_e32 v18, v18, v18
	v_mul_f32_e32 v19, v19, v19
	v_mul_f32_e32 v20, v20, v146
	v_mul_f32_e32 v21, v21, v146
	v_mul_f32_e32 v22, v22, v146
	v_mul_f32_e32 v23, v23, v146
	v_max_f32_e32 v20, 0, v20
	v_max_f32_e32 v21, 0, v21
	v_max_f32_e32 v22, 0, v22
	v_max_f32_e32 v23, 0, v23
	v_mul_f32_e32 v20, v20, v20
	v_mul_f32_e32 v21, v21, v21
	v_mul_f32_e32 v22, v22, v22
	v_mul_f32_e32 v23, v23, v23
	v_cvt_pk_bf16_f32 v154, v16, v17
	v_cvt_pk_bf16_f32 v155, v18, v19
	v_cvt_pk_bf16_f32 v156, v20, v21
	v_cvt_pk_bf16_f32 v157, v22, v23
	global_store_dwordx4 v[152:153], v[154:157], off
	s_nop 1
	v_lshl_add_u64 v[152:153], v[152:153], 0, s[22:23]
	s_waitcnt vmcnt(0)
; template <class Epi, class Sched>
; __device__ __forceinline__ void gemm_phase(LAS unsigned char* lds, const Gemm g, const Sched& S, const Epi& E) {
;     const int tid = threadIdx.x, wid = __builtin_amdgcn_readfirstlane(tid >> 6), lane = tid & 63, wr = wid >> 2, wc = wid & 3, fr = lane & 15, fq = lane >> 4;
;     const int nt = g.K / BK;
;     unsigned voffA[2], voffB[2];
; #pragma unroll
;     for (int i = 0; i < 2; ++i) { int R, C; stage_rc(tid * 16 + i * 8192, R, C); const int Rb = Epi::PERM ? ((R & ~31) + perm32(R & 31)) : R;
;         voffA[i] = (unsigned)(R * g.lda + C) * 2u; voffB[i] = (unsigned)(Rb * g.ldb + C) * 2u; }
;     const size_t kstep = (size_t)(BK * 2);
;     const size_t hstepA = (size_t)HALF * g.lda * 2, hstepB = (size_t)HALF * g.ldb * 2;
;     const size_t tstepA = 2 * hstepA, tstepB = 2 * hstepB;
;     const unsigned ldsw = (unsigned)wid * 1024u;
;     const int aoff = lds_byte(wr * 64 + fr, fq * 8), boff = lds_byte(wc * 32 + fr, fq * 8);
;     ...
;     Unit cur, nxt; int ui = 0;
;     if (!S.next(0, cur)) return;
;     f32x4 acc[2][2][4][2];
; #pragma unroll
;     for (int a = 0; a < 2; ++a)
; #pragma unroll
;         for (int b = 0; b < 2; ++b)
; #pragma unroll
;             for (int m = 0; m < 4; ++m)
; #pragma unroll
;                 for (int n = 0; n < 2; ++n) acc[a][b][m][n] = (f32x4){0.f, 0.f, 0.f, 0.f};
;     bf16x8 At[4][2], B0[2][2], B1[2][2];
;     const char* cA = (const char*)g.A + (size_t)cur.pm * tstepA; const char* cB = (const char*)g.Bt + (size_t)cur.pn * tstepB;
;     PG8_STAGE(PG8_SB(0, 0), cB, voffB); PG8_STAGE(PG8_SB(0, 1), cB + hstepB, voffB); PG8_STAGE(PG8_SA(0, 0), cA, voffA); PG8_STAGE(PG8_SA(0, 1), cA + hstepA, voffA);
;     if (wr == 1) PG8_BAR;
;     __device__ __forceinline__ void operator()(const f32x4 (&acc)[2][2][4][2], const Unit& u, int wr, int wc, int fr, int fq) const {
;     ...
;                 for (int bj = 0; bj < 2; ++bj) { f32x4 v0 = acc[ai][bj][m][0] * rs, v1 = acc[ai][bj][m][1] * rs;
;                     if (ACT == 1) {
; #pragma unroll
;                         for (int e = 0; e < 4; ++e) { const float a0 = fmaxf(v0[e], 0.f), a1 = fmaxf(v1[e], 0.f); v0[e] = a0 * a0; v1[e] = a1 * a1; } }
;                     u32x4 w; w.x = cvt_pk_bf16(v0[0], v0[1]); w.y = cvt_pk_bf16(v0[2], v0[3]); w.z = cvt_pk_bf16(v1[0], v1[1]); w.w = cvt_pk_bf16(v1[2], v1[3]);
;                     *(u32x4*)(rowp + bj * HALF) = w; } }
	v_mul_f32_e32 v24, v24, v147
	v_mul_f32_e32 v25, v25, v147
	v_mul_f32_e32 v26, v26, v147
	v_mul_f32_e32 v27, v27, v147
	v_max_f32_e32 v24, 0, v24
	v_max_f32_e32 v25, 0, v25
	v_max_f32_e32 v26, 0, v26
	v_max_f32_e32 v27, 0, v27
	v_mul_f32_e32 v24, v24, v24
	v_mul_f32_e32 v25, v25, v25
	v_mul_f32_e32 v26, v26, v26
	v_mul_f32_e32 v27, v27, v27
	v_mul_f32_e32 v28, v28, v147
	v_mul_f32_e32 v29, v29, v147
	v_mul_f32_e32 v30, v30, v147
	v_mul_f32_e32 v31, v31, v147
	v_max_f32_e32 v28, 0, v28
	v_max_f32_e32 v29, 0, v29
	v_max_f32_e32 v30, 0, v30
	v_max_f32_e32 v31, 0, v31
	v_mul_f32_e32 v28, v28, v28
	v_mul_f32_e32 v29, v29, v29
	v_mul_f32_e32 v30, v30, v30
	v_mul_f32_e32 v31, v31, v31
	v_cvt_pk_bf16_f32 v154, v24, v25
	v_cvt_pk_bf16_f32 v155, v26, v27
	v_cvt_pk_bf16_f32 v156, v28, v29
	v_cvt_pk_bf16_f32 v157, v30, v31
	global_store_dwordx4 v[152:153], v[154:157], off
	v_readfirstlane_b32 s5, v188
	v_lshrrev_b32_e32 v0, 5, v188
	v_lshrrev_b32_e32 v2, 1, v188
	v_and_b32_e32 v0, 4, v0
	v_bfe_u32 v1, v188, 2, 2
	v_and_b32_e32 v11, 24, v2
	v_or3_b32 v0, v0, v1, v11
	v_lshlrev_b32_e32 v1, 4, v188
	v_add_u32_e32 v8, 0x2000, v1
	v_lshrrev_b32_e32 v2, 7, v8
	s_movk_i32 s0, 0xe0
	v_and_b32_e32 v4, 32, v188
	v_and_or_b32 v3, v2, s0, v0
	v_bitop3_b32 v9, v1, v4, 48 bitop3:0x6c
	v_and_b32_e32 v10, 64, v188
	v_bfe_u32 v12, v188, 2, 4
	s_movk_i32 s0, 0xf0
	v_or_b32_e32 v1, v9, v10
	v_and_or_b32 v2, v2, s0, v12
	v_lshl_or_b32 v130, v2, 12, v1
	v_lshrrev_b32_e32 v2, 3, v188
	s_movk_i32 s0, 0x60
	v_and_or_b32 v0, v2, s0, v0
	s_movk_i32 s0, 0x70
	s_ashr_i32 s33, s2, 31
	v_lshl_or_b32 v132, v0, 12, v1
	v_and_or_b32 v0, v2, s0, v12
	s_lshr_b32 s0, s33, 29
	s_add_i32 s0, s2, s0
	s_lshr_b32 s10, s5, 6
	s_ashr_i32 s1, s0, 3
	s_and_b32 s0, s0, -8
	s_lshr_b32 s14, s5, 8
	s_lshl_b32 s3, s10, 10
	s_sub_i32 s0, s2, s0
	s_cmp_lt_i32 s0, 0
	s_movk_i32 s40, 0x101
	s_cselect_b32 s4, s40, 0x100
	s_mul_i32 s0, s0, s4
	s_add_i32 s0, s0, s1
	s_ashr_i32 s1, s0, 31
	s_lshr_b32 s1, s1, 26
	s_add_i32 s1, s0, s1
	s_ashr_i32 s4, s1, 6
	s_andn2_b32 s1, s1, 63
	s_sub_i32 s0, s0, s1
	s_bfe_u32 s1, s0, 0x10007
	s_add_i32 s1, s0, s1
	s_lshl_b32 s8, s4, 1
	s_bfe_i32 s4, s1, 0x80000
	s_and_b32 s1, s1, 0xfe
	s_sub_i32 s0, s0, s1
	s_sext_i32_i16 s4, s4
	s_sext_i32_i8 s0, s0
	s_lshr_b32 s4, s4, 1
	s_add_i32 s0, s8, s0
	s_ashr_i32 s1, s0, 31
	s_bfe_i64 s[16:17], s[4:5], 0x100000
	s_lshl_b64 s[8:9], s[0:1], 20
	s_lshl_b64 s[16:17], s[16:17], 20
	s_add_u32 s36, s66, s16
	s_addc_u32 s37, s67, s17
	s_add_i32 s41, s3, 0
	s_add_i32 m0, s41, 0x10000
	v_lshl_or_b32 v128, v3, 12, v1
	global_load_lds_dwordx4 v132, s[36:37]
	s_add_i32 m0, s41, 0x12000
	s_add_u32 s16, s36, 0x80000
	global_load_lds_dwordx4 v128, s[36:37]
	s_addc_u32 s17, s37, 0
	s_add_i32 m0, s41, 0x14000
	v_lshl_or_b32 v134, v0, 12, v1
	global_load_lds_dwordx4 v132, s[16:17]
	s_add_i32 m0, s41, 0x16000
	s_add_u32 s34, s12, s8
	s_addc_u32 s35, s13, s9
	s_add_i32 s42, s41, 0x2000
	global_load_lds_dwordx4 v128, s[16:17]
	s_mov_b32 m0, s41
	s_add_u32 s8, s34, 0x80000
	global_load_lds_dwordx4 v134, s[34:35]
	s_mov_b32 m0, s42
	s_addc_u32 s9, s35, 0
	s_add_i32 s43, s41, 0x4000
	global_load_lds_dwordx4 v130, s[34:35]
	s_mov_b32 m0, s43
	s_add_i32 s44, s41, 0x6000
	global_load_lds_dwordx4 v134, s[8:9]
	s_mov_b32 m0, s44
	v_mov_b32_e32 v133, 0
	global_load_lds_dwordx4 v130, s[8:9]
	v_mov_b32_e32 v129, v133
	v_mov_b32_e32 v135, v133
	v_mov_b32_e32 v131, v133
	s_cmp_eq_u32 s14, 1
	s_mov_b32 s45, 0
	v_lshl_add_u64 v[6:7], s[36:37], 0, v[132:133]
	v_lshl_add_u64 v[4:5], s[36:37], 0, v[128:129]
	v_lshl_add_u64 v[0:1], s[34:35], 0, v[134:135]
	s_cselect_b64 s[8:9], -1, 0
	s_cmp_lg_u32 s14, 1
	v_lshl_add_u64 v[2:3], s[34:35], 0, v[130:131]
	s_cbranch_scc1 .LBB0_927
	s_barrier
.LBB0_927:
	s_lshl_b32 s1, s10, 5
	s_mov_b64 s[10:11], 0x80
	s_and_b32 s18, s1, 0x60
	s_add_i32 m0, s41, 0x18000
	v_lshl_add_u64 v[6:7], v[6:7], 0, s[10:11]
	s_lshl_b32 s15, s14, 13
	s_lshl_b32 s19, s18, 7
	s_waitcnt vmcnt(2)
	s_barrier
	global_load_lds_dwordx4 v[6:7], off
	v_lshl_add_u64 v[4:5], v[4:5], 0, s[10:11]
	s_add_i32 m0, s41, 0x1a000
	s_add_i32 s46, s41, 0x8000
	s_add_i32 s47, s41, 0xa000
	global_load_lds_dwordx4 v[4:5], off
	v_lshl_add_u64 v[0:1], v[0:1], 0, s[10:11]
	s_mov_b32 m0, s46
	s_add_u32 s16, s36, 0x80080
	global_load_lds_dwordx4 v[0:1], off
	v_lshl_add_u64 v[0:1], v[2:3], 0, s[10:11]
	s_mov_b32 m0, s47
	s_addc_u32 s17, s37, 0
	global_load_lds_dwordx4 v[0:1], off
	s_add_i32 m0, s41, 0x1c000
	v_lshl_add_u64 v[0:1], s[16:17], 0, v[132:133]
	global_load_lds_dwordx4 v[0:1], off
	v_lshl_add_u64 v[0:1], s[16:17], 0, v[128:129]
	s_add_i32 m0, s41, 0x1e000
	s_sext_i32_i8 s1, s4
	global_load_lds_dwordx4 v[0:1], off
	v_and_b32_e32 v0, 15, v188
	v_lshlrev_b32_e32 v1, 1, v11
	v_lshlrev_b32_e32 v2, 2, v188
	v_lshlrev_b32_e32 v3, 6, v188
	s_movk_i32 s4, 0x3c0
	v_lshl_or_b32 v152, s14, 6, v0
	v_lshl_or_b32 v0, v0, 6, v1
	v_and_b32_e32 v2, 32, v2
	v_and_or_b32 v1, v3, s4, v1
	v_bitop3_b32 v153, s19, v1, v2 bitop3:0xf6
	v_lshlrev_b32_e32 v1, 9, v188
	v_bitop3_b32 v0, v0, s15, v2 bitop3:0xde
	v_and_b32_e32 v1, 0x70000, v1
	v_lshlrev_b32_e32 v2, 12, v12
	v_or3_b32 v1, v9, v1, v2
	v_add_u32_e32 v136, v1, v10
	v_lshlrev_b32_e32 v1, 5, v8
	s_waitcnt vmcnt(6)
	s_cmpk_lt_u32 s5, 0x100
	v_and_b32_e32 v1, 0xf0000, v1
	s_cselect_b64 s[14:15], -1, 0
	v_readlane_b32 s4, v249, 21
	v_or3_b32 v1, v9, v1, v2
	s_add_i32 s50, 0, 0x10000
	s_add_i32 s51, 0, 0x14000
	s_ashr_i32 s48, s4, 31
	s_mov_b32 s49, s4
	v_or_b32_e32 v154, s18, v11
	v_mov_b32_e32 v137, v133
	v_add_u32_e32 v138, v1, v10
	v_mov_b32_e32 v139, v133
	v_mov_b64_e32 v[140:141], 0x800
	v_mov_b64_e32 v[142:143], 0x7ff
	v_add_u32_e32 v155, s50, v153
	v_add_u32_e32 v156, s51, v153
	v_add_u32_e32 v157, 0, v0
	s_mov_b64 s[16:17], 0x200000
	s_mov_b32 s52, 0x200000
	s_mov_b64 s[18:19], 0x240000
	s_mov_b32 s53, 0x240000
	s_mov_b64 s[20:21], 0x280000
	s_mov_b32 s54, 0x280000
	s_mov_b64 s[22:23], 0x2c0000
	s_mov_b32 s55, 0x2c0000
	s_barrier
	v_readlane_b32 s5, v249, 22
	s_branch .LBB0_930

;     __host__ __device__ bool next(int i, Unit& u) const {
;         const long L = (long)i * G + c; if (L >= nwg) return false;
;         int wgid = (int)L; { const int q = nwg / NXCD, r = nwg % NXCD, xcd = wgid % NXCD, off = wgid / NXCD; wgid = (xcd < r ? xcd * (q + 1) : r * (q + 1) + (xcd - r) * q) + off; }
;         const int nig = WGM * nN, gid = wgid / nig, fm = gid * WGM, gsz = (nM - fm) < WGM ? (nM - fm) : WGM;
;         u.pm = fm + ((wgid % nig) % gsz); u.pn = (wgid % nig) / gsz; return true;
; template <class Epi, class Sched>
; __device__ __forceinline__ void gemm_phase(LAS unsigned char* lds, const Gemm g, const Sched& S, const Epi& E) {
;     ...
;         const bool has_next = S.next(ui + 1, nxt);
;         const char* nA = has_next ? (const char*)g.A + (size_t)nxt.pm * tstepA : cA; const char* nB = has_next ? (const char*)g.Bt + (size_t)nxt.pn * tstepB : cB;
.LBB0_930:
	s_add_i32 s45, s45, 1
	s_mul_i32 s4, s45, s48
	s_mul_hi_u32 s5, s45, s49
	s_add_i32 s5, s5, s4
	s_mul_i32 s4, s45, s49
	s_add_u32 s28, s4, s2
	s_addc_u32 s29, s5, s33
	v_cmp_gt_i64_e32 vcc, s[28:29], v[142:143]
	v_cmp_lt_i64_e64 s[4:5], s[28:29], v[140:141]
	s_cbranch_vccnz .LBB0_932
	s_ashr_i32 s24, s28, 31
	s_lshr_b32 s24, s24, 29
	s_add_i32 s24, s28, s24
	s_ashr_i32 s25, s24, 3
	s_and_b32 s24, s24, -8
	s_sub_i32 s24, s28, s24
	s_cmp_lt_i32 s24, 0
	s_cselect_b32 s26, s40, 0x100
	s_mul_i32 s24, s24, s26
	s_add_i32 s24, s24, s25
	s_ashr_i32 s25, s24, 31
	s_lshr_b32 s25, s25, 26
	s_add_i32 s25, s24, s25
	s_ashr_i32 s26, s25, 6
	s_lshl_b32 s26, s26, 1
	s_sub_i32 s27, 0x40, s26
	s_min_i32 s27, s27, 2
	s_abs_i32 s28, s27
	v_cvt_f32_u32_e32 v0, s28
	s_sub_i32 s30, 0, s28
	s_andn2_b32 s25, s25, 63
	s_sub_i32 s25, s24, s25
	v_rcp_iflag_f32_e32 v0, v0
	s_abs_i32 s24, s25
	s_xor_b32 s29, s25, s27
	s_ashr_i32 s29, s29, 31
	v_mul_f32_e32 v0, 0x4f7ffffe, v0
	v_cvt_u32_f32_e32 v0, v0
	s_nop 0
	v_readfirstlane_b32 s31, v0
	s_mul_i32 s30, s30, s31
	s_mul_hi_u32 s30, s31, s30
	s_add_i32 s31, s31, s30
	s_mul_hi_u32 s30, s24, s31
	s_mul_i32 s31, s30, s28
	s_sub_i32 s24, s24, s31
	s_add_i32 s38, s30, 1
	s_sub_i32 s31, s24, s28
	s_cmp_ge_u32 s24, s28
	s_cselect_b32 s30, s38, s30
	s_cselect_b32 s24, s31, s24
	s_add_i32 s31, s30, 1
	s_cmp_ge_u32 s24, s28
	s_cselect_b32 s24, s31, s30
	s_xor_b32 s24, s24, s29
	s_sub_i32 s24, s24, s29
	s_mul_i32 s27, s24, s27
	s_sub_i32 s25, s25, s27
	s_add_i32 s26, s26, s25
